# attention loop: hand-scheduled first half-step for tiles known live at the latch (QK MFMAs interleaved with exps, V loads behind freeing MFMAs, counted waits); K/Q fragment registers renamed
# speedup vs baseline: 1.0029x; 1.0029x over previous
.LBB0_300:
	s_or_b64 exec, exec, s[4:5]
	s_lshl_b32 s4, s3, 8
	v_readlane_b32 s5, v245, 15
	s_lshl_b32 s69, s3, 2
	s_ashr_i32 s3, s2, 31
	s_add_i32 s68, s4, s5
	s_lshl_b64 s[2:3], s[2:3], 2
	s_sub_u32 s2, s7, s2
	v_mov_b32_e32 v3, s11
	v_mov_b32_e32 v8, s89
	s_subb_u32 s3, s33, s3
	v_mov_b32_e32 v175, 0
	s_waitcnt lgkmcnt(0)
	s_barrier
	ds_read_b128 v[4:7], v3
	ds_read_b128 v[8:11], v8
	v_and_b32_e32 v185, 31, v19
	v_lshrrev_b32_e32 v3, 1, v19
	v_lshlrev_b32_e32 v172, 2, v2
	v_lshlrev_b32_e32 v12, 7, v185
	v_bitop3_b32 v2, v3, v2, 7 bitop3:0x6c
	v_mul_f32_e32 v18, s12, v235
	v_lshl_add_u32 v186, v2, 4, v12
	v_or_b32_e32 v2, s68, v185
	v_cvt_f32_i32_e32 v3, v172
	v_mul_f32_e32 v173, 0x42800000, v18
	s_mov_b32 s56, 0x41600000
	v_cvt_f32_u32_e32 v2, v2
	v_div_scale_f32 v58, s[2:3], v173, v173, s56
	v_cvt_f32_u32_e32 v13, s4
	v_rcp_f32_e32 v60, v58
	s_waitcnt lgkmcnt(1)
	v_max_f32_e32 v5, v5, v5
	v_max_f32_e32 v4, v4, v4
	v_sub_f32_e32 v187, v3, v2
	v_max_f32_e32 v2, v4, v5
	v_max3_f32 v2, v2, v6, v7
	v_fma_f32 v3, -v58, v60, 1.0
	v_add_f32_e32 v176, v187, v13
	s_waitcnt lgkmcnt(0)
	v_max3_f32 v23, v2, v8, v9
	v_fmac_f32_e32 v60, v3, v60
	v_pk_add_f32 v[2:3], v[176:177], s[14:15] op_sel_hi:[0,1]
	v_max3_f32 v23, v23, v10, v11
	v_and_b32_e32 v24, 0x7fffffff, v2
	s_mov_b32 s2, 0xf800000
	v_and_b32_e32 v25, 0x7fffffff, v3
	v_pk_add_f32 v[12:13], v[176:177], s[22:23] op_sel_hi:[0,1]
	v_pk_add_f32 v[14:15], v[176:177], s[24:25] op_sel_hi:[0,1]
	v_pk_add_f32 v[16:17], v[176:177], s[26:27] op_sel_hi:[0,1]
	v_add_f32_e32 v26, 1.0, v176
	v_and_b32_e32 v11, 0x7fffffff, v13
	v_and_b32_e32 v10, 0x7fffffff, v12
	v_and_b32_e32 v13, 0x7fffffff, v15
	v_and_b32_e32 v12, 0x7fffffff, v14
	v_and_b32_e32 v15, 0x7fffffff, v17
	v_and_b32_e32 v14, 0x7fffffff, v16
	v_and_b32_e32 v22, 0x7fffffff, v176
	v_pk_mul_f32 v[16:17], v[14:15], v[18:19] op_sel_hi:[1,0] neg_lo:[0,1] neg_hi:[0,1]
	v_pk_add_f32 v[8:9], v[176:177], s[20:21] op_sel_hi:[0,1]
	v_and_b32_e32 v9, 0x7fffffff, v9
	v_and_b32_e32 v8, 0x7fffffff, v8
	v_readlane_b32 s55, v245, 28
	v_pk_add_f32 v[4:5], v[176:177], s[16:17] op_sel_hi:[0,1]
	v_pk_add_f32 v[6:7], v[176:177], s[18:19] op_sel_hi:[0,1]
	v_xor_b32_e32 v188, 32, v186
	v_and_b32_e32 v5, 0x7fffffff, v5
	v_and_b32_e32 v4, 0x7fffffff, v4
	v_and_b32_e32 v7, 0x7fffffff, v7
	v_and_b32_e32 v6, 0x7fffffff, v6
	v_add_u32_e32 v61, 0, v188
	v_add_u32_e32 v189, s52, v186
	v_add_u32_e32 v192, s52, v188
	v_div_scale_f32 v59, s[4:5], s56, v173, s56
	v_pk_add_f32 v[42:43], v[176:177], s[28:29] op_sel_hi:[0,1]
	v_pk_add_f32 v[44:45], v[176:177], s[30:31] op_sel_hi:[0,1]
	v_pk_add_f32 v[46:47], v[176:177], s[34:35] op_sel_hi:[0,1]
	v_pk_add_f32 v[48:49], v[176:177], s[36:37] op_sel_hi:[0,1]
	v_pk_add_f32 v[50:51], v[176:177], s[38:39] op_sel_hi:[0,1]
	v_pk_add_f32 v[52:53], v[176:177], s[40:41] op_sel_hi:[0,1]
	v_pk_add_f32 v[54:55], v[176:177], s[42:43] op_sel_hi:[0,1]
	v_pk_add_f32 v[56:57], v[176:177], s[44:45] op_sel_hi:[0,1]
	v_and_b32_e32 v57, 0x7fffffff, v57
	v_and_b32_e32 v56, 0x7fffffff, v56
	v_and_b32_e32 v55, 0x7fffffff, v55
	v_and_b32_e32 v54, 0x7fffffff, v54
	v_and_b32_e32 v53, 0x7fffffff, v53
	v_and_b32_e32 v52, 0x7fffffff, v52
	v_and_b32_e32 v51, 0x7fffffff, v51
	v_and_b32_e32 v50, 0x7fffffff, v50
	v_and_b32_e32 v49, 0x7fffffff, v49
	v_and_b32_e32 v48, 0x7fffffff, v48
	v_and_b32_e32 v47, 0x7fffffff, v47
	v_and_b32_e32 v46, 0x7fffffff, v46
	v_and_b32_e32 v45, 0x7fffffff, v45
	s_waitcnt vmcnt(4)
	v_mul_f32_e32 v2, v23, v249
	v_mul_f32_e32 v3, 0x4f800000, v2
	v_cmp_gt_f32_e32 vcc, s2, v2
	v_and_b32_e32 v23, 0x7fffffff, v26
	v_and_b32_e32 v44, 0x7fffffff, v44
	v_cndmask_b32_e32 v21, v2, v3, vcc
	v_sqrt_f32_e32 v27, v21
	v_pk_mul_f32 v[2:3], v[22:23], v[18:19] op_sel_hi:[1,0] neg_lo:[0,1] neg_hi:[0,1]
	v_and_b32_e32 v43, 0x7fffffff, v43
	v_and_b32_e32 v42, 0x7fffffff, v42
	v_add_u32_e32 v14, -1, v27
	v_add_u32_e32 v15, 1, v27
	v_fma_f32 v22, -v14, v27, v21
	v_fma_f32 v23, -v15, v27, v21
	v_cmp_ge_f32_e64 s[2:3], 0, v22
	v_pk_mul_f32 v[96:97], v[42:43], v[18:19] op_sel_hi:[1,0] neg_lo:[0,1] neg_hi:[0,1]
	v_pk_mul_f32 v[94:95], v[44:45], v[18:19] op_sel_hi:[1,0] neg_lo:[0,1] neg_hi:[0,1]
	v_cndmask_b32_e64 v14, v27, v14, s[2:3]
	v_cmp_lt_f32_e64 s[2:3], 0, v23
	v_pk_mul_f32 v[92:93], v[46:47], v[18:19] op_sel_hi:[1,0] neg_lo:[0,1] neg_hi:[0,1]
	v_pk_mul_f32 v[90:91], v[48:49], v[18:19] op_sel_hi:[1,0] neg_lo:[0,1] neg_hi:[0,1]
	v_cndmask_b32_e64 v14, v14, v15, s[2:3]
	v_mul_f32_e32 v15, 0x37800000, v14
	v_cndmask_b32_e32 v14, v14, v15, vcc
	v_cmp_class_f32_e32 vcc, v21, v232
	v_pk_mul_f32 v[88:89], v[50:51], v[18:19] op_sel_hi:[1,0] neg_lo:[0,1] neg_hi:[0,1]
	v_pk_mul_f32 v[86:87], v[52:53], v[18:19] op_sel_hi:[1,0] neg_lo:[0,1] neg_hi:[0,1]
	v_cndmask_b32_e32 v14, v14, v21, vcc
	v_mul_f32_e32 v21, 0x3f828f5c, v14
	v_add_f32_e32 v246, 0x42000000, v21
	s_nop 0
	v_readfirstlane_b32 s98, v246
	v_fmaak_f32 v22, 2.0, v21, 0x42000000
	v_div_scale_f32 v23, s[2:3], v18, v18, v22
	v_rcp_f32_e32 v26, v23
	v_pk_mul_f32 v[14:15], v[12:13], v[18:19] op_sel_hi:[1,0] neg_lo:[0,1] neg_hi:[0,1]
	v_div_scale_f32 v12, vcc, v22, v18, v22
	v_fma_f32 v13, -v23, v26, 1.0
	v_fmac_f32_e32 v26, v13, v26
	v_mul_f32_e32 v13, v12, v26
	v_fma_f32 v27, -v23, v13, v12
	v_fmac_f32_e32 v13, v27, v26
	v_fma_f32 v12, -v23, v13, v12
	v_div_fmas_f32 v12, v12, v26, v13
	v_div_fixup_f32 v22, v12, v18, v22
	v_cvt_i32_f32_e32 v23, v22
	v_cmp_gt_f32_e32 vcc, s90, v22
	v_pk_mul_f32 v[12:13], v[10:11], v[18:19] op_sel_hi:[1,0] neg_lo:[0,1] neg_hi:[0,1]
	v_pk_mul_f32 v[10:11], v[8:9], v[18:19] op_sel_hi:[1,0] neg_lo:[0,1] neg_hi:[0,1]
	v_readfirstlane_b32 s2, v23
	s_add_i32 s12, s2, 1
	s_and_b64 s[2:3], vcc, exec
	s_cselect_b32 s2, s12, 0x2000
	s_add_i32 s12, s2, 62
	s_add_i32 s2, s2, -2
	s_ashr_i32 s12, s12, 6
	s_ashr_i32 s2, s2, 6
	s_xor_b32 s3, s69, 60
	s_min_i32 s77, s69, s12
	s_add_i32 s2, s2, 1
	s_min_i32 s2, s3, s2
	s_add_i32 s82, s77, 4
	s_add_u32 s12, s80, 0x30000
	s_addc_u32 s13, s81, 0
	s_add_u32 s12, s80, 0x60000
	v_readlane_b32 s13, v245, 27
	s_addc_u32 s13, s81, 0
	v_add_u32_e32 v26, 0, v186
	v_readlane_b32 s12, v245, 29
	v_readlane_b32 s12, v245, 30
	v_pk_mul_f32 v[8:9], v[6:7], v[18:19] op_sel_hi:[1,0] neg_lo:[0,1] neg_hi:[0,1]
	v_pk_mul_f32 v[6:7], v[4:5], v[18:19] op_sel_hi:[1,0] neg_lo:[0,1] neg_hi:[0,1]
	v_pk_mul_f32 v[4:5], v[24:25], v[18:19] op_sel_hi:[1,0] neg_lo:[0,1] neg_hi:[0,1]
	ds_read_b128 v[22:25], v26
	ds_read_b128 v[26:29], v26 offset:4096
	ds_read_b128 v[30:33], v61
	ds_read_b128 v[34:37], v189
	ds_read_b128 v[38:41], v192
	s_waitcnt lgkmcnt(1)
	v_mfma_f32_32x32x16_bf16 v[98:113], v[22:25], v[34:37], v[2:17]
	v_mul_f32_e32 v22, v59, v60
	v_fma_f32 v23, -v58, v22, v59
	v_fmac_f32_e32 v22, v23, v60
	v_mul_f32_e64 v84, v54, -v18
	v_mul_f32_e64 v85, v55, -v18
	v_pk_mul_f32 v[82:83], v[56:57], v[18:19] op_sel_hi:[1,0] neg_lo:[0,1] neg_hi:[0,1]
	v_fma_f32 v23, -v58, v22, v59
	s_mov_b64 vcc, s[4:5]
	v_mfma_f32_32x32x16_bf16 v[82:97], v[26:29], v[34:37], v[82:97]
	v_div_fmas_f32 v26, v23, v60, v22
	ds_read_b128 v[22:25], v61 offset:4096
	v_div_fixup_f32 v26, v26, v173, s56
	v_cmp_gt_f32_e32 vcc, s24, v21
	s_add_i32 s83, s82, s2
	s_cmp_lt_i32 s83, 1
	v_cndmask_b32_e32 v21, 0, v26, vcc
	s_waitcnt lgkmcnt(1)
	v_mfma_f32_32x32x16_bf16 v[98:113], v[30:33], v[38:41], v[98:113]
	v_min_f32_e32 v21, 0x42800000, v21
	s_nop 0
	v_readfirstlane_b32 s3, v21
	s_waitcnt lgkmcnt(0)
	v_mfma_f32_32x32x16_bf16 v[82:97], v[22:25], v[38:41], v[82:97]
	s_cbranch_scc1 .LBB0_350
	v_lshrrev_b32_e32 v21, 2, v19
	v_lshlrev_b32_e32 v19, 1, v19
	v_cvt_i32_f32_e32 v193, s3
	v_and_or_b32 v21, v21, 3, v172
	v_and_or_b32 v19, v19, 32, v20
	v_readfirstlane_b32 s99, v193
	v_lshl_or_b32 v19, v21, 6, v19
	v_mov_b32_e32 v50, v1
	v_mov_b32_e32 v51, v1
	v_mov_b32_e32 v64, v1
	v_mov_b32_e32 v65, v1
	v_xor_b32_e32 v178, 0x80000000, v18
	v_add_u32_e32 v195, 0x2000, v19
	v_mul_f32_e32 v196, 0x42000000, v18
	v_mul_f32_e32 v197, 0xc2000000, v18
	s_add_i32 s86, s2, s77
	v_mov_b32_e32 v52, v1
	v_mov_b32_e32 v53, v1
	v_mov_b32_e32 v54, v1
	v_mov_b32_e32 v55, v1
	v_mov_b32_e32 v56, v1
	v_mov_b32_e32 v57, v1
	v_mov_b32_e32 v58, v1
	v_mov_b32_e32 v59, v1
	v_mov_b32_e32 v60, v1
	v_mov_b32_e32 v61, v1
	v_mov_b32_e32 v62, v1
	v_mov_b32_e32 v63, v1
	v_mov_b64_e32 v[18:19], v[50:51]
	v_mov_b64_e32 v[80:81], v[64:65]
	v_mov_b64_e32 v[34:35], v[50:51]
	v_mov_b32_e32 v180, v178
	v_mov_b32_e32 v181, v178
	v_xor_b32_e32 v194, 64, v186
	s_sub_i32 s84, s69, s77
	s_or_b32 s85, s69, 3
	v_xor_b32_e32 v198, 0x60, v186
	s_add_i32 s86, s86, 4
	s_add_i32 s87, s77, 3
	s_mov_b32 s88, 0
	v_mov_b32_e32 v174, v1
	v_mov_b32_e32 v175, v1
	v_mov_b32_e32 v182, 0
	s_mov_b32 s89, s69
	v_mov_b64_e32 v[20:21], v[52:53]
	v_mov_b64_e32 v[22:23], v[54:55]
	v_mov_b64_e32 v[24:25], v[56:57]
	v_mov_b64_e32 v[26:27], v[58:59]
	v_mov_b64_e32 v[28:29], v[60:61]
	v_mov_b64_e32 v[30:31], v[62:63]
	v_mov_b64_e32 v[32:33], v[64:65]
	v_mov_b64_e32 v[78:79], v[62:63]
	v_mov_b64_e32 v[76:77], v[60:61]
	v_mov_b64_e32 v[74:75], v[58:59]
	v_mov_b64_e32 v[72:73], v[56:57]
	v_mov_b64_e32 v[70:71], v[54:55]
	v_mov_b64_e32 v[68:69], v[52:53]
	v_mov_b64_e32 v[66:67], v[50:51]
	v_mov_b64_e32 v[36:37], v[52:53]
	v_mov_b64_e32 v[38:39], v[54:55]
	v_mov_b64_e32 v[40:41], v[56:57]
	v_mov_b64_e32 v[42:43], v[58:59]
	v_mov_b64_e32 v[44:45], v[60:61]
	v_mov_b64_e32 v[46:47], v[62:63]
	v_mov_b64_e32 v[48:49], v[64:65]
	v_add_u32_e32 v254, s52, v194
	v_add_u32_e32 v255, s52, v198
	v_add_u32_e32 v114, s88, v194
	ds_read_b128 v[146:149], v114
	ds_read_b128 v[150:153], v114 offset:4096
	v_add_u32_e32 v114, s88, v198
	ds_read_b128 v[154:157], v114
	ds_read_b128 v[158:161], v114 offset:4096
	ds_read_b128 v[162:165], v254
	ds_read_b128 v[166:169], v255
	s_mov_b64 s[100:101], 0
	s_mov_b32 s90, 0
	s_add_i32 s2, s90, 2
	s_cmp_ge_i32 s2, s83
	s_mov_b64 s[2:3], -1
	s_cbranch_scc0 .LBB0_303

.Ldyn_back:
.LBB0_310:
	s_cmp_lg_u64 s[100:101], 0
	s_cbranch_scc1 .La_fast
	s_cmp_lt_i32 s90, s82
	s_cselect_b64 s[4:5], -1, 0
	s_cmp_lt_u32 s90, 4
	s_cselect_b64 s[2:3], -1, 0
	s_mov_b64 s[12:13], -1
	s_and_b64 vcc, exec, s[2:3]
	s_cbranch_vccnz .LBB0_312
	s_waitcnt lgkmcnt(1)
	v_mfma_f32_32x32x16_bf16 v[130:145], v[146:149], v[162:165], v[2:17]
	s_and_b64 s[4:5], s[4:5], exec
	s_cselect_b32 s4, 0, s77
	s_sub_i32 s4, s90, s4
	s_add_i32 s4, s4, -4
	s_cmp_ge_i32 s4, s99
	s_cselect_b64 s[12:13], -1, 0
	s_not_b64 s[4:5], s[12:13]
	v_mfma_f32_32x32x16_bf16 v[114:129], v[150:153], v[162:165], v[228:243]
	v_max3_f32 v246, v98, v97, v105
	v_exp_f32_e32 v246, v246
	s_waitcnt lgkmcnt(0)
	v_mfma_f32_32x32x16_bf16 v[130:145], v[154:157], v[166:169], v[130:145]
	v_mul_f32_e32 v246, 0x4f800000, v246
	v_cmp_ge_f32_e32 vcc, v246, v175
	v_mfma_f32_32x32x16_bf16 v[114:129], v[158:161], v[166:169], v[114:129]
	s_mov_b64 s[80:81], -1
	s_cmp_lg_u64 s[4:5], 0
	s_cbranch_scc1 .LBB0_319
	s_cmp_eq_u32 s99, 0
	s_cbranch_scc1 .Lq_fullA
	s_cmp_lg_u64 vcc, 0
	s_cbranch_scc1 .LBB0_319
	s_branch .Lq_fullA

.LBB0_314:
	s_waitcnt lgkmcnt(1)
	v_mfma_f32_32x32x16_bf16 v[130:145], v[146:149], v[162:165], v[2:17]
	v_mfma_f32_32x32x16_bf16 v[114:129], v[150:153], v[162:165], v[114:129]
	s_waitcnt lgkmcnt(0)
	v_mfma_f32_32x32x16_bf16 v[130:145], v[154:157], v[166:169], v[130:145]
	v_mfma_f32_32x32x16_bf16 v[114:129], v[158:161], v[166:169], v[114:129]
	s_and_b64 s[4:5], s[4:5], exec
	s_cselect_b32 s4, 0, s77
	s_sub_i32 s4, s90, s4
	s_add_i32 s4, s4, -4
	s_cmp_ge_i32 s4, s99
	s_cselect_b64 s[12:13], -1, 0
	s_or_b64 s[12:13], s[2:3], s[12:13]
	s_not_b64 s[4:5], s[12:13]
	s_mov_b64 s[80:81], -1
	s_cbranch_scc1 .LBB0_319
	s_cmp_lt_u32 s90, 4
	s_cbranch_scc1 .Lq_fullA
	s_cmp_eq_u32 s99, 0
	s_cbranch_scc1 .Lq_fullA
	v_max3_f32 v146, v98, v97, v105
	v_exp_f32_e32 v146, v146
	s_nop 0
	v_mul_f32_e32 v146, 0x4f800000, v146
	v_cmp_ge_f32_e32 vcc, v146, v175
	s_cmp_lg_u64 vcc, 0
	s_cbranch_scc1 .LBB0_319

.La_pv_tail:
	v_cvt_pk_bf16_f32 v146, v82, v83
	v_cvt_pk_bf16_f32 v147, v84, v85
	v_cvt_pk_bf16_f32 v148, v86, v87
	v_cvt_pk_bf16_f32 v149, v88, v89
	v_cvt_pk_bf16_f32 v150, v90, v91
	v_cvt_pk_bf16_f32 v151, v92, v93
	v_cvt_pk_bf16_f32 v152, v94, v95
	v_cvt_pk_bf16_f32 v153, v96, v97
	s_nop 0
	v_mfma_f32_32x32x16_bf16 v[50:65], v[154:157], v[146:149], v[50:65]
	v_add_f32_e32 v154, v98, v100
	v_add_f32_e32 v155, v99, v101
	v_add_f32_e32 v156, v102, v104
	v_add_f32_e32 v157, v103, v105
	v_add_f32_e32 v162, v106, v108
	v_add_f32_e32 v163, v107, v109
	v_pk_add_f32 v[164:165], v[110:111], v[112:113]
	v_mfma_f32_32x32x16_bf16 v[18:33], v[200:203], v[146:149], v[18:33]
	v_add_f32_e32 v146, v82, v84
	v_add_f32_e32 v147, v83, v85
	v_add_f32_e32 v148, v86, v88
	v_add_f32_e32 v149, v87, v89
	v_add_f32_e32 v166, v90, v92
	v_add_f32_e32 v167, v91, v93
	v_pk_add_f32 v[168:169], v[94:95], v[96:97]
	v_mfma_f32_32x32x16_bf16 v[50:65], v[158:161], v[150:153], v[50:65]
	v_add_f32_e32 v154, v154, v156
	v_add_f32_e32 v155, v155, v157
	v_add_f32_e32 v156, v162, v164
	v_add_f32_e32 v157, v163, v165
	v_add_f32_e32 v146, v146, v148
	v_add_f32_e32 v147, v147, v149
	v_pk_add_f32 v[148:149], v[166:167], v[168:169]
	v_mfma_f32_32x32x16_bf16 v[18:33], v[204:207], v[150:153], v[18:33]
	v_add_f32_e32 v150, v154, v156
	v_add_f32_e32 v151, v155, v157
	v_add_f32_e32 v146, v146, v148
	v_add_f32_e32 v147, v147, v149
	v_add_f32_e32 v146, v146, v150
	v_add_f32_e32 v147, v147, v151
	v_add_f32_e32 v146, v146, v147
	v_add_f32_e32 v175, v175, v146

.Ldma_done:
	s_cmp_eq_u32 s87, s90
	s_cselect_b64 s[12:13], -1, 0
	s_or_b64 s[12:13], s[2:3], s[12:13]
	s_mov_b64 s[2:3], -1
	s_cbranch_scc1 .Lb_nform
	s_add_i32 s100, s88, 0x4000
	s_and_b32 s100, s100, 0xffff
	v_add_u32_e32 v82, s100, v186
	ds_read_b128 v[146:149], v82
	ds_read_b128 v[150:153], v82 offset:4096
	v_add_u32_e32 v82, s100, v188
	ds_read_b128 v[154:157], v82
	ds_read_b128 v[158:161], v82 offset:4096
	ds_read_b128 v[162:165], v189
	ds_read_b128 v[166:169], v192
	v_sub_f32_e32 v17, v17, v173
	v_sub_f32_e32 v16, v16, v173
	v_sub_f32_e32 v15, v15, v173
	v_sub_f32_e32 v14, v14, v173
	v_sub_f32_e32 v13, v13, v173
	v_sub_f32_e32 v12, v12, v173
	v_sub_f32_e32 v11, v11, v173
	v_sub_f32_e32 v10, v10, v173
	v_sub_f32_e32 v9, v9, v173
	v_sub_f32_e32 v8, v8, v173
	v_sub_f32_e32 v7, v7, v173
	v_sub_f32_e32 v6, v6, v173
	v_sub_f32_e32 v5, v5, v173
	v_sub_f32_e32 v4, v4, v173
	v_sub_f32_e32 v3, v3, v173
	v_sub_f32_e32 v2, v2, v173
	v_sub_f32_e32 v243, v243, v173
	v_sub_f32_e32 v242, v242, v173
	v_sub_f32_e32 v241, v241, v173
	v_sub_f32_e32 v240, v240, v173
	v_sub_f32_e32 v239, v239, v173
	v_sub_f32_e32 v238, v238, v173
	v_sub_f32_e32 v237, v237, v173
	v_sub_f32_e32 v236, v236, v173
	v_sub_f32_e32 v235, v235, v173
	v_sub_f32_e32 v234, v234, v173
	v_sub_f32_e32 v233, v233, v173
	v_sub_f32_e32 v232, v232, v173
	v_sub_f32_e32 v231, v231, v173
	v_sub_f32_e32 v230, v230, v173
	v_sub_f32_e32 v229, v229, v173
	v_sub_f32_e32 v228, v228, v173
	s_add_i32 s12, s90, 1
	s_add_i32 s2, s88, 0x4000
	s_and_b32 s88, s2, 0xffff
	s_cmp_ge_i32 s12, s83
	s_cbranch_scc1 .LBB0_339
	s_cmp_lt_u32 s90, 3
	s_mov_b64 s[2:3], -1
	s_cbranch_scc1 .LBB0_336
	s_waitcnt lgkmcnt(1)
	v_mfma_f32_32x32x16_bf16 v[98:113], v[146:149], v[162:165], v[2:17]
	v_max3_f32 v246, v130, v129, v137
	v_exp_f32_e32 v246, v246
	v_mfma_f32_32x32x16_bf16 v[82:97], v[150:153], v[162:165], v[228:243]
	s_waitcnt lgkmcnt(0)
	v_mfma_f32_32x32x16_bf16 v[98:113], v[154:157], v[166:169], v[98:113]
	v_mul_f32_e32 v246, 0x4f800000, v246
	v_cmp_ge_f32_e32 vcc, v246, v174
	v_mfma_f32_32x32x16_bf16 v[82:97], v[158:161], v[166:169], v[82:97]
	s_mov_b64 s[2:3], -1
	s_cmp_lg_u64 s[4:5], 0
	s_cbranch_scc1 .LBB0_345
	s_cmp_lt_u32 s90, 4
	s_cbranch_scc1 .Lq_fullB
	s_cmp_eq_u32 s99, 0
	s_cbranch_scc1 .Lq_fullB
	s_cmp_lg_u64 vcc, 0
	s_cbranch_scc1 .LBB0_345
	s_branch .Lq_fullB

.LBB0_324:
	s_add_i32 s100, s88, 0x4000
	s_and_b32 s100, s100, 0xffff
	v_add_u32_e32 v82, s100, v186
	ds_read_b128 v[146:149], v82
	ds_read_b128 v[150:153], v82 offset:4096
	v_add_u32_e32 v82, s100, v188
	ds_read_b128 v[154:157], v82
	ds_read_b128 v[158:161], v82 offset:4096
	ds_read_b128 v[162:165], v189
	ds_read_b128 v[166:169], v192
	v_sub_f32_e32 v17, v17, v173
	v_sub_f32_e32 v16, v16, v173
	v_sub_f32_e32 v15, v15, v173
	v_sub_f32_e32 v14, v14, v173
	v_sub_f32_e32 v13, v13, v173
	v_sub_f32_e32 v12, v12, v173
	v_sub_f32_e32 v11, v11, v173
	v_sub_f32_e32 v10, v10, v173
	v_sub_f32_e32 v9, v9, v173
	v_sub_f32_e32 v8, v8, v173
	v_sub_f32_e32 v7, v7, v173
	v_sub_f32_e32 v6, v6, v173
	v_sub_f32_e32 v5, v5, v173
	v_sub_f32_e32 v4, v4, v173
	v_sub_f32_e32 v3, v3, v173
	v_sub_f32_e32 v2, v2, v173
	s_add_i32 s12, s90, 1
	s_cbranch_execnz .LBB0_323

.LBB0_334:
	s_add_i32 s2, s88, 0
	v_add_u32_e32 v82, s2, v186
	ds_read_b128 v[146:149], v82
	ds_read_b128 v[150:153], v82 offset:4096
	v_add_u32_e32 v82, s2, v188
	ds_read_b128 v[154:157], v82
	ds_read_b128 v[158:161], v82 offset:4096
	ds_read_b128 v[162:165], v189
	ds_read_b128 v[166:169], v192
.Lqk_B_noreads:
	s_cmp_lt_u32 s90, 3
	s_mov_b64 s[2:3], -1
	s_cbranch_scc1 .LBB0_336
	s_waitcnt lgkmcnt(1)
	v_mfma_f32_32x32x16_bf16 v[98:113], v[146:149], v[162:165], v[2:17]
	s_cmp_lt_i32 s12, s82
	s_cselect_b64 vcc, -1, 0
	v_cndmask_b32_e32 v246, v197, v196, vcc
	v_pk_add_f32 v[242:243], v[246:247], v[16:17] op_sel_hi:[0,1]
	v_pk_add_f32 v[240:241], v[246:247], v[14:15] op_sel_hi:[0,1]
	v_pk_add_f32 v[238:239], v[246:247], v[12:13] op_sel_hi:[0,1]
	v_pk_add_f32 v[236:237], v[246:247], v[10:11] op_sel_hi:[0,1]
	v_pk_add_f32 v[234:235], v[246:247], v[8:9] op_sel_hi:[0,1]
	v_pk_add_f32 v[232:233], v[246:247], v[6:7] op_sel_hi:[0,1]
	v_pk_add_f32 v[230:231], v[246:247], v[4:5] op_sel_hi:[0,1]
	v_pk_add_f32 v[228:229], v[246:247], v[2:3] op_sel_hi:[0,1]
	s_nop 1
	v_mfma_f32_32x32x16_bf16 v[82:97], v[150:153], v[162:165], v[228:243]
	s_waitcnt lgkmcnt(0)
	v_mfma_f32_32x32x16_bf16 v[98:113], v[154:157], v[166:169], v[98:113]
	v_mfma_f32_32x32x16_bf16 v[82:97], v[158:161], v[166:169], v[82:97]
	s_branch .LBB0_339

.LBB0_338:
	s_waitcnt lgkmcnt(1)
	v_mfma_f32_32x32x16_bf16 v[98:113], v[146:149], v[162:165], v[2:17]
	v_mfma_f32_32x32x16_bf16 v[82:97], v[150:153], v[162:165], v[82:97]
	s_waitcnt lgkmcnt(0)
	v_mfma_f32_32x32x16_bf16 v[98:113], v[154:157], v[166:169], v[98:113]
	v_mfma_f32_32x32x16_bf16 v[82:97], v[158:161], v[166:169], v[82:97]

.Ldyn_post_back:
	s_mov_b32 s90, s12
	s_mov_b64 s[100:101], 0
	s_cmp_lt_u32 s90, 4
	s_cbranch_scc1 .La_dec_done
	s_cmp_lt_i32 s90, s82
	s_cselect_b32 s4, 0, s77
	s_sub_i32 s4, s90, s4
	s_add_i32 s4, s4, -4
	s_cmp_ge_i32 s4, s99
	s_cselect_b64 s[12:13], -1, 0
	s_not_b64 s[4:5], s[12:13]
	s_cbranch_scc1 .La_dec_nolook
	s_cmp_eq_u32 s99, 0
	s_cbranch_scc1 .La_dec_done
	v_max3_f32 v246, v98, v97, v105
	v_exp_f32_e32 v246, v246
	s_nop 0
	v_mul_f32_e32 v246, 0x4f800000, v246
	v_cmp_ge_f32_e64 s[100:101], v246, v175
	s_branch .La_dec_done
.La_dec_nolook:
	s_mov_b64 s[100:101], -1
.La_dec_done:
	v_add_u32_e32 v114, s88, v194
	ds_read_b128 v[146:149], v114
	ds_read_b128 v[150:153], v114 offset:4096
	v_add_u32_e32 v114, s88, v198
	ds_read_b128 v[154:157], v114
	ds_read_b128 v[158:161], v114 offset:4096
	ds_read_b128 v[162:165], v254
	ds_read_b128 v[166:169], v255
	s_add_i32 s2, s90, 2
	s_cmp_ge_i32 s2, s83
	s_mov_b64 s[2:3], -1
	s_cbranch_scc1 .LBB0_302
	s_branch .LBB0_303
.La_fast:
	v_add_u32_e32 v199, s88, v195
	s_mov_b64 s[2:3], 0
	s_waitcnt lgkmcnt(1)
	v_mfma_f32_32x32x16_bf16 v[130:145], v[146:149], v[162:165], v[2:17]
	v_exp_f32_e32 v98, v98
	v_exp_f32_e32 v99, v99
	v_exp_f32_e32 v100, v100
	v_mfma_f32_32x32x16_bf16 v[114:129], v[150:153], v[162:165], v[228:243]
	ds_read_b64_tr_b16 v[146:147], v199 offset:0
	ds_read_b64_tr_b16 v[148:149], v199 offset:0x200
	ds_read_b64_tr_b16 v[162:163], v199 offset:0x1000
	ds_read_b64_tr_b16 v[164:165], v199 offset:0x1200
	ds_read_b64_tr_b16 v[150:151], v199 offset:0x400
	ds_read_b64_tr_b16 v[152:153], v199 offset:0x600
	ds_read_b64_tr_b16 v[200:201], v199 offset:0x1800
	ds_read_b64_tr_b16 v[202:203], v199 offset:0x1a00
	ds_read_b64_tr_b16 v[204:205], v199 offset:0x1c00
	ds_read_b64_tr_b16 v[206:207], v199 offset:0x1e00
	v_exp_f32_e32 v101, v101
	v_exp_f32_e32 v102, v102
	v_exp_f32_e32 v103, v103
	s_waitcnt lgkmcnt(10)
	v_mfma_f32_32x32x16_bf16 v[130:145], v[154:157], v[166:169], v[130:145]
	v_exp_f32_e32 v104, v104
	v_exp_f32_e32 v105, v105
	v_exp_f32_e32 v106, v106
	v_mfma_f32_32x32x16_bf16 v[114:129], v[158:161], v[166:169], v[114:129]
	ds_read_b64_tr_b16 v[166:167], v199 offset:0x1400
	ds_read_b64_tr_b16 v[168:169], v199 offset:0x1600
	ds_read_b64_tr_b16 v[154:155], v199 offset:0x800
	ds_read_b64_tr_b16 v[156:157], v199 offset:0xa00
	ds_read_b64_tr_b16 v[158:159], v199 offset:0xc00
	ds_read_b64_tr_b16 v[160:161], v199 offset:0xe00
	v_exp_f32_e32 v107, v107
	v_exp_f32_e32 v108, v108
	v_exp_f32_e32 v109, v109
	v_exp_f32_e32 v110, v110
	v_exp_f32_e32 v111, v111
	v_exp_f32_e32 v112, v112
	v_exp_f32_e32 v113, v113
	v_cvt_pk_bf16_f32 v208, v98, v99
	v_cvt_pk_bf16_f32 v209, v100, v101
	v_cvt_pk_bf16_f32 v210, v102, v103
	v_cvt_pk_bf16_f32 v211, v104, v105
	v_cvt_pk_bf16_f32 v212, v106, v107
	v_cvt_pk_bf16_f32 v213, v108, v109
	v_cvt_pk_bf16_f32 v214, v110, v111
	v_cvt_pk_bf16_f32 v215, v112, v113
	s_waitcnt lgkmcnt(6)
	s_nop 0
	v_mfma_f32_32x32x16_bf16 v[50:65], v[146:149], v[208:211], v[50:65]
	v_exp_f32_e32 v82, v82
	v_exp_f32_e32 v83, v83
	v_exp_f32_e32 v84, v84
	v_exp_f32_e32 v85, v85
	v_mfma_f32_32x32x16_bf16 v[18:33], v[162:165], v[208:211], v[18:33]
	v_exp_f32_e32 v86, v86
	v_exp_f32_e32 v87, v87
	v_exp_f32_e32 v88, v88
	v_exp_f32_e32 v89, v89
	v_mfma_f32_32x32x16_bf16 v[50:65], v[150:153], v[212:215], v[50:65]
	v_exp_f32_e32 v90, v90
	v_exp_f32_e32 v91, v91
	v_exp_f32_e32 v92, v92
	v_exp_f32_e32 v93, v93
	s_waitcnt lgkmcnt(0)
	v_mfma_f32_32x32x16_bf16 v[18:33], v[166:169], v[212:215], v[18:33]
	v_exp_f32_e32 v94, v94
	v_exp_f32_e32 v95, v95
	v_exp_f32_e32 v96, v96
	v_exp_f32_e32 v97, v97
	s_branch .La_pv_tail

.Ldyn_update:
	v_mov_b32_e32 v246, 0x18080
	ds_read_b32 v246, v246
	v_rcp_f32_e32 v247, v173
	s_waitcnt lgkmcnt(0)
	v_mul_f32_e32 v246, v246, v247
	v_mul_f32_e32 v246, 0x42800800, v246
	v_min_f32_e32 v246, 0x46000000, v246
	v_cvt_i32_f32_e32 v246, v246
	s_nop 0
	v_readfirstlane_b32 s56, v246
	s_add_i32 s56, s56, 2
	s_add_i32 s12, s56, 62
	s_ashr_i32 s12, s12, 6
	s_add_i32 s13, s56, -2
	s_ashr_i32 s13, s13, 6
	s_add_i32 s13, s13, 1
	s_max_i32 s12, s12, s99
	s_max_i32 s13, s13, s99
	s_max_i32 s12, s12, 3
	s_max_i32 s13, s13, 3
	s_sub_i32 s57, s83, s82
	s_min_i32 s12, s12, s77
	s_min_i32 s13, s13, s57
	s_mov_b32 s77, s12
	s_add_i32 s82, s77, 4
	s_add_i32 s83, s82, s13
	s_mov_b32 s86, s83
	s_sub_i32 s84, s69, s77
	s_add_i32 s87, s77, 3
	s_branch .Ldyn_back
